# v18 plus 2-deep kv prefetch in the sample compression loop
# baseline (speedup 1.0000x reference)
.LBB0_694:
	s_or_b64 exec, exec, s[8:9]
	v_mov_b32_e32 v0, s29
	s_waitcnt lgkmcnt(0)
	s_barrier
	ds_read_b32 v0, v0
	s_mov_b64 s[8:9], -1
	s_waitcnt lgkmcnt(0)
	v_cmp_lt_i32_e32 vcc, s30, v0
	v_readfirstlane_b32 s22, v0
	s_cbranch_vccnz .LBB0_689
	s_cmp_gt_i32 s22, 35
	s_mov_b64 s[18:19], -1
	s_cbranch_scc0 .LBB0_715
	v_mov_b64_e32 v[0:1], s[0:1]
	flat_load_dwordx2 v[2:3], v[0:1] offset:64
	s_add_i32 s9, s22, 0xffdc
	s_and_b32 s8, s9, 0xffff
	s_mul_i32 s8, s8, 0xf0f1
	s_lshr_b32 s8, s8, 20
	s_mul_i32 s10, s8, 17
	s_sub_i32 s9, s9, s10
	s_mul_i32 s9, s9, 31
	s_and_b32 s9, s9, 0xffff
	v_add_u32_e32 v21, s9, v168
	v_min_i32_e32 v23, 0x1ff, v21
	v_min_i32_e32 v4, 0x1fb, v21
	v_min_i32_e32 v5, 0x1f7, v21
	v_min_i32_e32 v6, 0x1f3, v21
	v_min_i32_e32 v7, 0x1ef, v21
	v_min_i32_e32 v8, 0x1eb, v21
	v_lshrrev_b32_e32 v9, 29, v23
	v_add_u32_e32 v25, 4, v4
	v_add_u32_e32 v27, 8, v5
	v_add_u32_e32 v29, 12, v6
	v_add_u32_e32 v31, 16, v7
	v_add_u32_e32 v32, 20, v8
	v_add_u32_e32 v4, v23, v9
	v_lshrrev_b32_e32 v5, 29, v25
	v_lshrrev_b32_e32 v6, 29, v27
	v_lshrrev_b32_e32 v7, 29, v29
	v_lshrrev_b32_e32 v8, 29, v31
	v_lshrrev_b32_e32 v9, 29, v32
	s_lshl_b32 s23, s8, 6
	v_ashrrev_i32_e32 v4, 3, v4
	v_add_u32_e32 v5, v25, v5
	v_add_u32_e32 v6, v27, v6
	v_add_u32_e32 v7, v29, v7
	v_add_u32_e32 v8, v31, v8
	v_add_u32_e32 v9, v32, v9
	flat_load_dwordx2 v[0:1], v[0:1] offset:16
	v_add_u32_e32 v4, s23, v4
	v_ashrrev_i32_e32 v10, 3, v5
	v_ashrrev_i32_e32 v11, 3, v6
	v_ashrrev_i32_e32 v7, 3, v7
	v_ashrrev_i32_e32 v12, 3, v8
	v_ashrrev_i32_e32 v9, 3, v9
	v_ashrrev_i32_e32 v5, 31, v4
	v_add_u32_e32 v6, s23, v10
	v_add_u32_e32 v8, s23, v11
	v_add_u32_e32 v10, s23, v7
	v_add_u32_e32 v12, s23, v12
	v_add_u32_e32 v14, s23, v9
	v_ashrrev_i32_e32 v7, 31, v6
	v_ashrrev_i32_e32 v9, 31, v8
	v_ashrrev_i32_e32 v11, 31, v10
	v_ashrrev_i32_e32 v13, 31, v12
	v_ashrrev_i32_e32 v15, 31, v14
	v_min_i32_e32 v33, 0x1e7, v21
	v_add_u32_e32 v44, 24, v33
	v_lshlrev_b32_e32 v46, 4, v32
	v_bfe_i32 v35, v32, 27, 1
	v_lshrrev_b32_e32 v32, 29, v44
	v_add_u32_e32 v32, v44, v32
	v_ashrrev_i32_e32 v32, 3, v32
	v_add_u32_e32 v32, s23, v32
	v_ashrrev_i32_e32 v33, 31, v32
	v_min_i32_e32 v21, 0x1e3, v21
	v_add_u32_e32 v45, 28, v21
	v_lshrrev_b32_e32 v36, 29, v45
	v_lshlrev_b32_e32 v34, 4, v23
	v_bfe_i32 v23, v23, 27, 1
	v_lshrrev_b32_e32 v21, 25, v23
	v_lshlrev_b32_e32 v23, 4, v25
	v_bfe_i32 v25, v25, 27, 1
	v_add_u32_e32 v21, v34, v21
	v_lshrrev_b32_e32 v25, 25, v25
	v_and_b32_e32 v21, 0xffffff80, v21
	v_add_u32_e32 v25, v23, v25
	v_sub_u32_e32 v34, v34, v21
	v_and_b32_e32 v21, 0xffffff80, v25
	v_lshlrev_b32_e32 v38, 4, v27
	v_bfe_i32 v27, v27, 27, 1
	v_lshrrev_b32_e32 v27, 25, v27
	v_lshlrev_b32_e32 v41, 4, v31
	s_waitcnt vmcnt(0) lgkmcnt(0)
	v_lshl_add_u64 v[4:5], v[4:5], 2, v[2:3]
	v_lshl_add_u64 v[6:7], v[6:7], 2, v[2:3]
	v_lshl_add_u64 v[8:9], v[8:9], 2, v[2:3]
	v_lshl_add_u64 v[10:11], v[10:11], 2, v[2:3]
	v_lshl_add_u64 v[12:13], v[12:13], 2, v[2:3]
	v_lshl_add_u64 v[14:15], v[14:15], 2, v[2:3]
	flat_load_dword v20, v[4:5]
	flat_load_dword v22, v[6:7]
	flat_load_dword v24, v[8:9]
	flat_load_dword v26, v[10:11]
	flat_load_dword v28, v[12:13]
	flat_load_dword v30, v[14:15]
	v_lshl_add_u64 v[32:33], v[32:33], 2, v[2:3]
	global_load_dwordx4 v[4:7], v[100:101], off
	global_load_dwordx4 v[8:11], v[102:103], off
	global_load_dwordx4 v[12:15], v[104:105], off
	global_load_dwordx4 v[16:19], v[106:107], off
	v_bfe_i32 v31, v31, 27, 1
	flat_load_dword v32, v[32:33]
	v_lshrrev_b32_e32 v33, 25, v35
	v_add_u32_e32 v35, v45, v36
	v_ashrrev_i32_e32 v35, 3, v35
	v_add_u32_e32 v36, s23, v35
	v_ashrrev_i32_e32 v37, 31, v36
	v_lshl_add_u64 v[2:3], v[36:37], 2, v[2:3]
	flat_load_dword v2, v[2:3]
	v_sub_u32_e32 v36, v23, v21
	v_ashrrev_i32_e32 v35, 31, v34
	v_lshlrev_b64 v[34:35], 12, v[34:35]
	v_ashrrev_i32_e32 v37, 31, v36
	v_add_u32_e32 v27, v38, v27
	v_lshlrev_b64 v[36:37], 12, v[36:37]
	s_mov_b32 s17, s11
	v_lshrrev_b32_e32 v31, 25, v31
	v_add_u32_e32 v33, v46, v33
	v_and_b32_e32 v3, 0xffffff80, v27
	v_add_u32_e32 v31, v41, v31
	v_sub_u32_e32 v38, v38, v3
	v_and_b32_e32 v3, 0xffffff80, v33
	v_and_b32_e32 v27, 0xffffff80, v31
	v_lshlrev_b32_e32 v39, 4, v29
	v_bfe_i32 v29, v29, 27, 1
	v_lshrrev_b32_e32 v29, 25, v29
	v_add_u32_e32 v29, v39, v29
	v_and_b32_e32 v25, 0xffffff80, v29
	v_sub_u32_e32 v40, v39, v25
	v_sub_u32_e32 v42, v41, v27
	v_ashrrev_i32_e32 v39, 31, v38
	v_ashrrev_i32_e32 v41, 31, v40
	v_ashrrev_i32_e32 v43, 31, v42
	v_lshlrev_b64 v[38:39], 12, v[38:39]
	v_lshlrev_b64 v[40:41], 12, v[40:41]
	v_lshlrev_b64 v[42:43], 12, v[42:43]
	s_mov_b32 s10, 0
	s_waitcnt vmcnt(0) lgkmcnt(0)
	v_ashrrev_i32_e32 v21, 31, v20
	v_ashrrev_i32_e32 v23, 31, v22
	v_lshlrev_b64 v[20:21], 19, v[20:21]
	v_lshlrev_b64 v[22:23], 19, v[22:23]
	v_lshl_add_u64 v[20:21], v[0:1], 0, v[20:21]
	v_lshl_add_u64 v[22:23], v[0:1], 0, v[22:23]
	v_lshl_add_u64 v[20:21], v[20:21], 0, v[34:35]
	v_lshl_add_u64 v[22:23], v[22:23], 0, v[36:37]
	v_lshl_add_u64 v[20:21], v[20:21], 0, s[14:15]
	v_lshl_add_u64 v[22:23], v[22:23], 0, s[14:15]
	v_lshl_add_u64 v[20:21], v[20:21], 0, s[16:17]
	v_ashrrev_i32_e32 v31, 31, v30
	v_lshl_add_u64 v[22:23], v[22:23], 0, s[16:17]
	v_lshl_add_u64 v[148:149], v[20:21], 0, v[96:97]
	v_sub_u32_e32 v20, v46, v3
	v_lshl_add_u64 v[150:151], v[22:23], 0, v[96:97]
	v_ashrrev_i32_e32 v21, 31, v20
	v_lshlrev_b64 v[22:23], 19, v[30:31]
	v_lshl_add_u64 v[22:23], v[0:1], 0, v[22:23]
	v_lshlrev_b64 v[20:21], 12, v[20:21]
	v_lshl_add_u64 v[20:21], v[22:23], 0, v[20:21]
	v_lshl_add_u64 v[20:21], v[20:21], 0, s[14:15]
	v_lshl_add_u64 v[20:21], v[20:21], 0, s[16:17]
	v_lshl_add_u64 v[158:159], v[20:21], 0, v[96:97]
	v_bfe_i32 v20, v44, 27, 1
	v_lshlrev_b32_e32 v3, 4, v44
	v_lshrrev_b32_e32 v20, 25, v20
	v_add_u32_e32 v20, v3, v20
	v_and_b32_e32 v20, 0xffffff80, v20
	v_ashrrev_i32_e32 v33, 31, v32
	v_sub_u32_e32 v20, v3, v20
	v_ashrrev_i32_e32 v21, 31, v20
	v_lshlrev_b64 v[22:23], 19, v[32:33]
	v_lshl_add_u64 v[22:23], v[0:1], 0, v[22:23]
	v_lshlrev_b64 v[20:21], 12, v[20:21]
	v_lshl_add_u64 v[20:21], v[22:23], 0, v[20:21]
	v_lshl_add_u64 v[20:21], v[20:21], 0, s[14:15]
	v_lshl_add_u64 v[20:21], v[20:21], 0, s[16:17]
	v_lshl_add_u64 v[160:161], v[20:21], 0, v[96:97]
	v_bfe_i32 v21, v45, 27, 1
	v_lshlrev_b32_e32 v20, 4, v45
	v_lshrrev_b32_e32 v21, 25, v21
	v_add_u32_e32 v21, v20, v21
	v_and_b32_e32 v21, 0xffffff80, v21
	v_ashrrev_i32_e32 v25, 31, v24
	v_ashrrev_i32_e32 v27, 31, v26
	v_ashrrev_i32_e32 v29, 31, v28
	v_ashrrev_i32_e32 v3, 31, v2
	v_sub_u32_e32 v20, v20, v21
	v_lshlrev_b64 v[24:25], 19, v[24:25]
	v_lshlrev_b64 v[26:27], 19, v[26:27]
	v_lshlrev_b64 v[28:29], 19, v[28:29]
	v_ashrrev_i32_e32 v21, 31, v20
	v_lshlrev_b64 v[2:3], 19, v[2:3]
	v_lshl_add_u64 v[24:25], v[0:1], 0, v[24:25]
	v_lshl_add_u64 v[26:27], v[0:1], 0, v[26:27]
	v_lshl_add_u64 v[28:29], v[0:1], 0, v[28:29]
	v_lshl_add_u64 v[0:1], v[0:1], 0, v[2:3]
	v_lshlrev_b64 v[2:3], 12, v[20:21]
	v_lshl_add_u64 v[24:25], v[24:25], 0, v[38:39]
	v_lshl_add_u64 v[26:27], v[26:27], 0, v[40:41]
	v_lshl_add_u64 v[28:29], v[28:29], 0, v[42:43]
	v_lshl_add_u64 v[0:1], v[0:1], 0, v[2:3]
	v_lshl_add_u64 v[24:25], v[24:25], 0, s[14:15]
	v_lshl_add_u64 v[26:27], v[26:27], 0, s[14:15]
	v_lshl_add_u64 v[28:29], v[28:29], 0, s[14:15]
	v_lshl_add_u64 v[0:1], v[0:1], 0, s[14:15]
	v_lshl_add_u64 v[24:25], v[24:25], 0, s[16:17]
	v_lshl_add_u64 v[26:27], v[26:27], 0, s[16:17]
	v_lshl_add_u64 v[28:29], v[28:29], 0, s[16:17]
	v_lshl_add_u64 v[0:1], v[0:1], 0, s[16:17]
	v_lshl_add_u64 v[152:153], v[24:25], 0, v[96:97]
	v_lshl_add_u64 v[154:155], v[26:27], 0, v[96:97]
	v_lshl_add_u64 v[156:157], v[28:29], 0, v[96:97]
	v_lshl_add_u64 v[162:163], v[0:1], 0, v[96:97]
	global_load_dwordx4 v[92:95], v[148:149], off
	global_load_dwordx4 v[88:91], v[150:151], off
	global_load_dwordx4 v[84:87], v[152:153], off
	global_load_dwordx4 v[80:83], v[154:155], off
	global_load_dwordx4 v[76:79], v[156:157], off
	global_load_dwordx4 v[72:75], v[158:159], off
	global_load_dwordx4 v[68:71], v[160:161], off
	global_load_dwordx4 v[64:67], v[162:163], off
	s_movk_i32 s10, 0x1000
	v_lshl_add_u64 v[246:247], v[148:149], 0, s[10:11]
	v_lshl_add_u64 v[242:243], v[150:151], 0, s[10:11]
	v_lshl_add_u64 v[238:239], v[152:153], 0, s[10:11]
	v_lshl_add_u64 v[234:235], v[154:155], 0, s[10:11]
	v_lshl_add_u64 v[230:231], v[156:157], 0, s[10:11]
	v_lshl_add_u64 v[222:223], v[158:159], 0, s[10:11]
	v_lshl_add_u64 v[218:219], v[160:161], 0, s[10:11]
	v_lshl_add_u64 v[214:215], v[162:163], 0, s[10:11]
	global_load_dwordx4 v[246:249], v[246:247], off
	global_load_dwordx4 v[242:245], v[242:243], off
	global_load_dwordx4 v[238:241], v[238:239], off
	global_load_dwordx4 v[234:237], v[234:235], off
	global_load_dwordx4 v[230:233], v[230:231], off
	global_load_dwordx4 v[222:225], v[222:223], off
	global_load_dwordx4 v[218:221], v[218:219], off
	global_load_dwordx4 v[214:217], v[214:215], off
	s_mov_b32 s10, 0
	ds_write_b128 v169, v[4:7]
	ds_write_b128 v169, v[8:11] offset:8192
	ds_write_b128 v169, v[12:15] offset:16384
	ds_write_b128 v169, v[16:19] offset:24576
	s_waitcnt lgkmcnt(0)
	v_mov_b32_e32 v0, 0
	s_mov_b32 s17, 0x8000
	v_mov_b32_e32 v1, v0
	v_mov_b32_e32 v2, v0
	v_mov_b32_e32 v3, v0
	v_mov_b32_e32 v4, v0
	v_mov_b32_e32 v5, v0
	v_mov_b32_e32 v6, v0
	v_mov_b32_e32 v7, v0
	v_mov_b32_e32 v8, v0
	v_mov_b32_e32 v9, v0
	v_mov_b32_e32 v10, v0
	v_mov_b32_e32 v11, v0
	v_mov_b32_e32 v12, v0
	v_mov_b32_e32 v13, v0
	v_mov_b32_e32 v14, v0
	v_mov_b32_e32 v15, v0
	v_mov_b32_e32 v32, v0
	v_mov_b32_e32 v33, v0
	v_mov_b32_e32 v34, v0
	v_mov_b32_e32 v35, v0
	v_mov_b32_e32 v36, v0
	v_mov_b32_e32 v37, v0
	v_mov_b32_e32 v38, v0
	v_mov_b32_e32 v39, v0
	v_mov_b32_e32 v40, v0
	v_mov_b32_e32 v41, v0
	v_mov_b32_e32 v42, v0
	v_mov_b32_e32 v43, v0
	v_mov_b32_e32 v44, v0
	v_mov_b32_e32 v45, v0
	v_mov_b32_e32 v46, v0
	v_mov_b32_e32 v47, v0
	v_mov_b32_e32 v16, v0
	v_mov_b32_e32 v17, v0
	v_mov_b32_e32 v18, v0
	v_mov_b32_e32 v19, v0
	v_mov_b32_e32 v20, v0
	v_mov_b32_e32 v21, v0
	v_mov_b32_e32 v22, v0
	v_mov_b32_e32 v23, v0
	v_mov_b32_e32 v24, v0
	v_mov_b32_e32 v25, v0
	v_mov_b32_e32 v26, v0
	v_mov_b32_e32 v27, v0
	v_mov_b32_e32 v28, v0
	v_mov_b32_e32 v29, v0
	v_mov_b32_e32 v30, v0
	v_mov_b32_e32 v31, v0
	v_mov_b32_e32 v48, v0
	v_mov_b32_e32 v49, v0
	v_mov_b32_e32 v50, v0
	v_mov_b32_e32 v51, v0
	v_mov_b32_e32 v52, v0
	v_mov_b32_e32 v53, v0
	v_mov_b32_e32 v54, v0
	v_mov_b32_e32 v55, v0
	v_mov_b32_e32 v56, v0
	v_mov_b32_e32 v57, v0
	v_mov_b32_e32 v58, v0
	v_mov_b32_e32 v59, v0
	v_mov_b32_e32 v60, v0
	v_mov_b32_e32 v61, v0
	v_mov_b32_e32 v62, v0
	v_mov_b32_e32 v63, v0
	s_waitcnt lgkmcnt(0)
	s_barrier
.LBB0_697:
	s_and_b32 s19, s10, 1
	s_mul_i32 s20, s19, 0x1200
	s_add_i32 s18, s10, 1
	v_lshl_add_u32 v98, s19, 15, v171
	s_add_i32 s19, s24, s20
	s_waitcnt vmcnt(15)
	v_cvt_pk_bf16_f32 v92, v92, v93
	v_cvt_pk_bf16_f32 v93, v94, v95
	s_waitcnt vmcnt(14)
	v_cvt_pk_bf16_f32 v88, v88, v89
	v_cvt_pk_bf16_f32 v89, v90, v91
	s_waitcnt vmcnt(8)
	v_cvt_pk_bf16_f32 v64, v64, v65
	v_cvt_pk_bf16_f32 v65, v66, v67
	v_add3_u32 v66, s19, v170, v174
	s_cmp_lg_u32 s10, 15
	v_cvt_pk_bf16_f32 v84, v84, v85
	v_cvt_pk_bf16_f32 v85, v86, v87
	v_cvt_pk_bf16_f32 v80, v80, v81
	v_cvt_pk_bf16_f32 v81, v82, v83
	v_cvt_pk_bf16_f32 v76, v76, v77
	v_cvt_pk_bf16_f32 v77, v78, v79
	v_cvt_pk_bf16_f32 v72, v72, v73
	v_cvt_pk_bf16_f32 v73, v74, v75
	ds_write2_b64 v66, v[92:93], v[88:89] offset1:72
	ds_write2_b64 v66, v[84:85], v[80:81] offset0:144 offset1:216
	v_add_u32_e32 v66, 0x800, v66
	s_cselect_b32 s10, s18, 15
	s_add_i32 s20, s18, 1
	s_min_u32 s20, s20, 15
	v_cvt_pk_bf16_f32 v68, v68, v69
	v_cvt_pk_bf16_f32 v69, v70, v71
	ds_write2_b64 v66, v[76:77], v[72:73] offset0:32 offset1:104
	ds_write2_b64 v66, v[68:69], v[64:65] offset0:176 offset1:248
	v_add_lshl_u32 v64, s10, v175, 4
	v_add_lshl_u32 v66, s10, v176, 4
	v_add_lshl_u32 v68, s10, v177, 4
	v_add_lshl_u32 v70, s10, v178, 4
	v_ashrrev_i32_e32 v65, 31, v64
	v_ashrrev_i32_e32 v67, 31, v66
	v_ashrrev_i32_e32 v69, 31, v68
	v_ashrrev_i32_e32 v71, 31, v70
	v_lshlrev_b64 v[64:65], 10, v[64:65]
	s_lshl_b32 s10, s20, 12
	v_lshlrev_b64 v[66:67], 10, v[66:67]
	v_lshlrev_b64 v[68:69], 10, v[68:69]
	v_lshlrev_b64 v[70:71], 10, v[70:71]
	v_lshl_add_u64 v[64:65], v[108:109], 0, v[64:65]
	v_lshl_add_u64 v[72:73], v[148:149], 0, s[10:11]
	v_lshl_add_u64 v[74:75], v[150:151], 0, s[10:11]
	v_lshl_add_u64 v[76:77], v[152:153], 0, s[10:11]
	v_lshl_add_u64 v[78:79], v[154:155], 0, s[10:11]
	v_lshl_add_u64 v[66:67], v[110:111], 0, v[66:67]
	v_lshl_add_u64 v[68:69], v[108:109], 0, v[68:69]
	v_lshl_add_u64 v[70:71], v[112:113], 0, v[70:71]
	global_load_dwordx4 v[182:185], v[64:65], off
	global_load_dwordx4 v[186:189], v[66:67], off
	global_load_dwordx4 v[190:193], v[68:69], off
	global_load_dwordx4 v[194:197], v[70:71], off
	v_lshl_add_u64 v[198:199], v[156:157], 0, s[10:11]
	v_lshl_add_u64 v[200:201], v[158:159], 0, s[10:11]
	v_lshl_add_u64 v[202:203], v[160:161], 0, s[10:11]
	v_lshl_add_u64 v[204:205], v[162:163], 0, s[10:11]
	global_load_dwordx4 v[92:95], v[72:73], off
	global_load_dwordx4 v[88:91], v[74:75], off
	global_load_dwordx4 v[84:87], v[76:77], off
	global_load_dwordx4 v[80:83], v[78:79], off
	s_nop 0
	global_load_dwordx4 v[76:79], v[198:199], off
	global_load_dwordx4 v[72:75], v[200:201], off
	global_load_dwordx4 v[68:71], v[202:203], off
	global_load_dwordx4 v[64:67], v[204:205], off
	s_waitcnt lgkmcnt(0)
	v_add3_u32 v145, s19, v172, v173
	ds_read_b128 v[198:201], v98
	ds_read_b128 v[202:205], v145
	ds_read_b128 v[206:209], v98 offset:1024
	ds_read_b128 v[210:213], v145 offset:32
	s_waitcnt lgkmcnt(2)
	v_mfma_f32_32x32x16_bf16 v[48:63], v[198:201], v[202:205], v[48:63]
	s_and_b32 s19, s17, 0x8000
	s_add_i32 s17, s17, 0x8000
	s_mov_b32 s10, s18
	s_cmp_eq_u32 s18, 16
	s_waitcnt lgkmcnt(1)
	v_mfma_f32_32x32x16_bf16 v[16:31], v[206:209], v[202:205], v[16:31]
	ds_read_b128 v[198:201], v98 offset:2048
	ds_read_b128 v[206:209], v98 offset:3072
	s_waitcnt lgkmcnt(1)
	v_mfma_f32_32x32x16_bf16 v[32:47], v[198:201], v[202:205], v[32:47]
	s_waitcnt lgkmcnt(0)
	v_mfma_f32_32x32x16_bf16 v[0:15], v[206:209], v[202:205], v[0:15]
	ds_read_b128 v[198:201], v98 offset:4096
	ds_read_b128 v[202:205], v98 offset:5120
	s_waitcnt lgkmcnt(1)
	v_mfma_f32_32x32x16_bf16 v[48:63], v[198:201], v[210:213], v[48:63]
	s_waitcnt lgkmcnt(0)
	v_mfma_f32_32x32x16_bf16 v[16:31], v[202:205], v[210:213], v[16:31]
	ds_read_b128 v[198:201], v98 offset:6144
	ds_read_b128 v[202:205], v98 offset:7168
	s_waitcnt lgkmcnt(1)
	v_mfma_f32_32x32x16_bf16 v[32:47], v[198:201], v[210:213], v[32:47]
	s_waitcnt lgkmcnt(0)
	v_mfma_f32_32x32x16_bf16 v[0:15], v[202:205], v[210:213], v[0:15]
	ds_read_b128 v[198:201], v98 offset:8192
	ds_read_b128 v[202:205], v145 offset:64
	ds_read_b128 v[206:209], v98 offset:9216
	ds_read_b128 v[210:213], v145 offset:96
	s_waitcnt lgkmcnt(2)
	v_mfma_f32_32x32x16_bf16 v[48:63], v[198:201], v[202:205], v[48:63]
	s_waitcnt lgkmcnt(1)
	v_mfma_f32_32x32x16_bf16 v[16:31], v[206:209], v[202:205], v[16:31]
	ds_read_b128 v[198:201], v98 offset:10240
	ds_read_b128 v[206:209], v98 offset:11264
	s_waitcnt lgkmcnt(1)
	v_mfma_f32_32x32x16_bf16 v[32:47], v[198:201], v[202:205], v[32:47]
	s_waitcnt lgkmcnt(0)
	v_mfma_f32_32x32x16_bf16 v[0:15], v[206:209], v[202:205], v[0:15]
	ds_read_b128 v[198:201], v98 offset:12288
	ds_read_b128 v[202:205], v98 offset:13312
	s_waitcnt lgkmcnt(1)
	v_mfma_f32_32x32x16_bf16 v[48:63], v[198:201], v[210:213], v[48:63]
	s_waitcnt lgkmcnt(0)
	v_mfma_f32_32x32x16_bf16 v[16:31], v[202:205], v[210:213], v[16:31]
	ds_read_b128 v[198:201], v98 offset:14336
	ds_read_b128 v[202:205], v98 offset:15360
	v_add_u32_e32 v98, s19, v169
	s_waitcnt vmcnt(11)
	ds_write_b128 v98, v[182:185]
	s_waitcnt vmcnt(10)
	ds_write_b128 v98, v[186:189] offset:8192
	s_waitcnt vmcnt(9)
	ds_write_b128 v98, v[190:193] offset:16384
	s_waitcnt vmcnt(8)
	ds_write_b128 v98, v[194:197] offset:24576
	s_waitcnt lgkmcnt(0)
	s_waitcnt lgkmcnt(0)
	s_barrier
	v_mfma_f32_32x32x16_bf16 v[32:47], v[198:201], v[210:213], v[32:47]
	v_mfma_f32_32x32x16_bf16 v[0:15], v[202:205], v[210:213], v[0:15]
	s_and_b32 s19, s10, 1
	s_mul_i32 s20, s19, 0x1200
	s_add_i32 s18, s10, 1
	v_lshl_add_u32 v98, s19, 15, v171
	s_add_i32 s19, s24, s20
	s_waitcnt vmcnt(15)
	v_cvt_pk_bf16_f32 v246, v246, v247
	v_cvt_pk_bf16_f32 v247, v248, v249
	s_waitcnt vmcnt(14)
	v_cvt_pk_bf16_f32 v242, v242, v243
	v_cvt_pk_bf16_f32 v243, v244, v245
	s_waitcnt vmcnt(8)
	v_cvt_pk_bf16_f32 v214, v214, v215
	v_cvt_pk_bf16_f32 v215, v216, v217
	v_add3_u32 v216, s19, v170, v174
	s_cmp_lg_u32 s10, 15
	v_cvt_pk_bf16_f32 v238, v238, v239
	v_cvt_pk_bf16_f32 v239, v240, v241
	v_cvt_pk_bf16_f32 v234, v234, v235
	v_cvt_pk_bf16_f32 v235, v236, v237
	v_cvt_pk_bf16_f32 v230, v230, v231
	v_cvt_pk_bf16_f32 v231, v232, v233
	v_cvt_pk_bf16_f32 v222, v222, v223
	v_cvt_pk_bf16_f32 v223, v224, v225
	ds_write2_b64 v216, v[246:247], v[242:243] offset1:72
	ds_write2_b64 v216, v[238:239], v[234:235] offset0:144 offset1:216
	v_add_u32_e32 v216, 0x800, v216
	s_cselect_b32 s10, s18, 15
	s_add_i32 s20, s18, 1
	s_min_u32 s20, s20, 15
	v_cvt_pk_bf16_f32 v218, v218, v219
	v_cvt_pk_bf16_f32 v219, v220, v221
	ds_write2_b64 v216, v[230:231], v[222:223] offset0:32 offset1:104
	ds_write2_b64 v216, v[218:219], v[214:215] offset0:176 offset1:248
	v_add_lshl_u32 v214, s10, v175, 4
	v_add_lshl_u32 v216, s10, v176, 4
	v_add_lshl_u32 v218, s10, v177, 4
	v_add_lshl_u32 v220, s10, v178, 4
	v_ashrrev_i32_e32 v215, 31, v214
	v_ashrrev_i32_e32 v217, 31, v216
	v_ashrrev_i32_e32 v219, 31, v218
	v_ashrrev_i32_e32 v221, 31, v220
	v_lshlrev_b64 v[214:215], 10, v[214:215]
	s_lshl_b32 s10, s20, 12
	v_lshlrev_b64 v[216:217], 10, v[216:217]
	v_lshlrev_b64 v[218:219], 10, v[218:219]
	v_lshlrev_b64 v[220:221], 10, v[220:221]
	v_lshl_add_u64 v[214:215], v[108:109], 0, v[214:215]
	v_lshl_add_u64 v[222:223], v[148:149], 0, s[10:11]
	v_lshl_add_u64 v[224:225], v[150:151], 0, s[10:11]
	v_lshl_add_u64 v[230:231], v[152:153], 0, s[10:11]
	v_lshl_add_u64 v[232:233], v[154:155], 0, s[10:11]
	v_lshl_add_u64 v[216:217], v[110:111], 0, v[216:217]
	v_lshl_add_u64 v[218:219], v[108:109], 0, v[218:219]
	v_lshl_add_u64 v[220:221], v[112:113], 0, v[220:221]
	global_load_dwordx4 v[182:185], v[214:215], off
	global_load_dwordx4 v[186:189], v[216:217], off
	global_load_dwordx4 v[190:193], v[218:219], off
	global_load_dwordx4 v[194:197], v[220:221], off
	v_lshl_add_u64 v[198:199], v[156:157], 0, s[10:11]
	v_lshl_add_u64 v[200:201], v[158:159], 0, s[10:11]
	v_lshl_add_u64 v[202:203], v[160:161], 0, s[10:11]
	v_lshl_add_u64 v[204:205], v[162:163], 0, s[10:11]
	global_load_dwordx4 v[246:249], v[222:223], off
	global_load_dwordx4 v[242:245], v[224:225], off
	global_load_dwordx4 v[238:241], v[230:231], off
	global_load_dwordx4 v[234:237], v[232:233], off
	s_nop 0
	global_load_dwordx4 v[230:233], v[198:199], off
	global_load_dwordx4 v[222:225], v[200:201], off
	global_load_dwordx4 v[218:221], v[202:203], off
	global_load_dwordx4 v[214:217], v[204:205], off
	s_waitcnt lgkmcnt(0)
	v_add3_u32 v145, s19, v172, v173
	ds_read_b128 v[198:201], v98
	ds_read_b128 v[202:205], v145
	ds_read_b128 v[206:209], v98 offset:1024
	ds_read_b128 v[210:213], v145 offset:32
	s_waitcnt lgkmcnt(2)
	v_mfma_f32_32x32x16_bf16 v[48:63], v[198:201], v[202:205], v[48:63]
	s_and_b32 s19, s17, 0x8000
	s_add_i32 s17, s17, 0x8000
	s_mov_b32 s10, s18
	s_cmp_eq_u32 s18, 16
	s_waitcnt lgkmcnt(1)
	v_mfma_f32_32x32x16_bf16 v[16:31], v[206:209], v[202:205], v[16:31]
	ds_read_b128 v[198:201], v98 offset:2048
	ds_read_b128 v[206:209], v98 offset:3072
	s_waitcnt lgkmcnt(1)
	v_mfma_f32_32x32x16_bf16 v[32:47], v[198:201], v[202:205], v[32:47]
	s_waitcnt lgkmcnt(0)
	v_mfma_f32_32x32x16_bf16 v[0:15], v[206:209], v[202:205], v[0:15]
	ds_read_b128 v[198:201], v98 offset:4096
	ds_read_b128 v[202:205], v98 offset:5120
	s_waitcnt lgkmcnt(1)
	v_mfma_f32_32x32x16_bf16 v[48:63], v[198:201], v[210:213], v[48:63]
	s_waitcnt lgkmcnt(0)
	v_mfma_f32_32x32x16_bf16 v[16:31], v[202:205], v[210:213], v[16:31]
	ds_read_b128 v[198:201], v98 offset:6144
	ds_read_b128 v[202:205], v98 offset:7168
	s_waitcnt lgkmcnt(1)
	v_mfma_f32_32x32x16_bf16 v[32:47], v[198:201], v[210:213], v[32:47]
	s_waitcnt lgkmcnt(0)
	v_mfma_f32_32x32x16_bf16 v[0:15], v[202:205], v[210:213], v[0:15]
	ds_read_b128 v[198:201], v98 offset:8192
	ds_read_b128 v[202:205], v145 offset:64
	ds_read_b128 v[206:209], v98 offset:9216
	ds_read_b128 v[210:213], v145 offset:96
	s_waitcnt lgkmcnt(2)
	v_mfma_f32_32x32x16_bf16 v[48:63], v[198:201], v[202:205], v[48:63]
	s_waitcnt lgkmcnt(1)
	v_mfma_f32_32x32x16_bf16 v[16:31], v[206:209], v[202:205], v[16:31]
	ds_read_b128 v[198:201], v98 offset:10240
	ds_read_b128 v[206:209], v98 offset:11264
	s_waitcnt lgkmcnt(1)
	v_mfma_f32_32x32x16_bf16 v[32:47], v[198:201], v[202:205], v[32:47]
	s_waitcnt lgkmcnt(0)
	v_mfma_f32_32x32x16_bf16 v[0:15], v[206:209], v[202:205], v[0:15]
	ds_read_b128 v[198:201], v98 offset:12288
	ds_read_b128 v[202:205], v98 offset:13312
	s_waitcnt lgkmcnt(1)
	v_mfma_f32_32x32x16_bf16 v[48:63], v[198:201], v[210:213], v[48:63]
	s_waitcnt lgkmcnt(0)
	v_mfma_f32_32x32x16_bf16 v[16:31], v[202:205], v[210:213], v[16:31]
	ds_read_b128 v[198:201], v98 offset:14336
	ds_read_b128 v[202:205], v98 offset:15360
	v_add_u32_e32 v98, s19, v169
	s_waitcnt vmcnt(11)
	ds_write_b128 v98, v[182:185]
	s_waitcnt vmcnt(10)
	ds_write_b128 v98, v[186:189] offset:8192
	s_waitcnt vmcnt(9)
	ds_write_b128 v98, v[190:193] offset:16384
	s_waitcnt vmcnt(8)
	ds_write_b128 v98, v[194:197] offset:24576
	s_waitcnt lgkmcnt(0)
	s_waitcnt lgkmcnt(0)
	s_barrier
	v_mfma_f32_32x32x16_bf16 v[32:47], v[198:201], v[210:213], v[32:47]
	v_mfma_f32_32x32x16_bf16 v[0:15], v[202:205], v[210:213], v[0:15]
	s_cbranch_scc0 .LBB0_697
	s_waitcnt vmcnt(1)
	flat_load_dwordx4 v[68:71], v[116:117]
	flat_load_dwordx4 v[72:75], v[118:119]
	flat_load_dwordx4 v[76:79], v[120:121]
	s_nop 5
	ds_bpermute_b32 v88, v166, v32
	ds_bpermute_b32 v89, v166, v33
	ds_bpermute_b32 v90, v166, v34
	ds_bpermute_b32 v91, v166, v35
	ds_bpermute_b32 v92, v166, v36
	ds_bpermute_b32 v93, v166, v37
	ds_bpermute_b32 v94, v166, v38
	ds_bpermute_b32 v95, v166, v39
	ds_bpermute_b32 v148, v166, v40
	ds_bpermute_b32 v149, v166, v41
	ds_bpermute_b32 v150, v166, v42
	ds_bpermute_b32 v151, v166, v43
	flat_load_dwordx4 v[32:35], v[122:123]
	global_load_dwordx2 v[36:37], v[124:125], off
	global_load_dwordx2 v[38:39], v[124:125], off offset:16
	global_load_dwordx2 v[64:65], v[124:125], off offset:32
	global_load_dwordx2 v[66:67], v[124:125], off offset:48
	global_load_dwordx2 v[40:41], v[126:127], off
	global_load_dwordx2 v[42:43], v[126:127], off offset:16
	global_load_dwordx2 v[80:81], v[128:129], off
	global_load_dwordx2 v[82:83], v[128:129], off offset:16
	flat_load_dwordx4 v[84:87], v[130:131]
	s_waitcnt lgkmcnt(0)
	v_pk_add_f32 v[50:51], v[50:51], v[90:91]
	v_pk_add_f32 v[52:53], v[52:53], v[92:93]
	v_pk_add_f32 v[48:49], v[48:49], v[88:89]
	v_pk_add_f32 v[54:55], v[54:55], v[94:95]
	v_pk_add_f32 v[56:57], v[56:57], v[148:149]
	ds_bpermute_b32 v44, v166, v44
	ds_bpermute_b32 v45, v166, v45
	v_pk_add_f32 v[58:59], v[58:59], v[150:151]
	ds_bpermute_b32 v46, v166, v46
	ds_bpermute_b32 v47, v166, v47
	ds_bpermute_b32 v0, v166, v0
	s_waitcnt lgkmcnt(0)
	v_pk_add_f32 v[44:45], v[60:61], v[44:45]
	ds_bpermute_b32 v1, v166, v1
	ds_bpermute_b32 v2, v166, v2
	ds_bpermute_b32 v3, v166, v3
	ds_bpermute_b32 v4, v166, v4
	ds_bpermute_b32 v5, v166, v5
	s_waitcnt lgkmcnt(0)
	v_pk_add_f32 v[0:1], v[16:17], v[0:1]
	ds_bpermute_b32 v8, v166, v8
	ds_bpermute_b32 v9, v166, v9
	ds_bpermute_b32 v10, v166, v10
	v_pk_add_f32 v[4:5], v[20:21], v[4:5]
	ds_bpermute_b32 v11, v166, v11
	ds_bpermute_b32 v12, v166, v12
	s_waitcnt lgkmcnt(0)
	v_pk_add_f32 v[8:9], v[24:25], v[8:9]
	ds_bpermute_b32 v13, v166, v13
	v_pk_add_f32 v[10:11], v[26:27], v[10:11]
	s_waitcnt lgkmcnt(0)
	v_pk_add_f32 v[12:13], v[28:29], v[12:13]
	s_waitcnt vmcnt(0)
	v_pk_add_f32 v[50:51], v[70:71], v[50:51]
	v_pk_add_f32 v[52:53], v[72:73], v[52:53]
	v_pk_add_f32 v[48:49], v[68:69], v[48:49]
	v_pk_mul_f32 v[68:69], v[50:51], v[50:51]
	v_pk_mul_f32 v[70:71], v[52:53], v[52:53]
	v_fmamk_f32 v68, v68, 0xbdd2d3e7, v181
	v_fmamk_f32 v69, v69, 0xbdd2d3e7, v181
	v_fmamk_f32 v70, v70, 0xbdd2d3e7, v181
	v_fmamk_f32 v71, v71, 0xbdd2d3e7, v181
	v_mul_f32_e32 v68, v50, v68
	v_mul_f32_e32 v69, v51, v69
	v_mul_f32_e32 v70, v52, v70
	v_mul_f32_e32 v71, v53, v71
	v_exp_f32_e32 v68, v68
	v_exp_f32_e32 v69, v69
	v_exp_f32_e32 v70, v70
	v_exp_f32_e32 v71, v71
	v_add_f32_e32 v68, 1.0, v68
	v_add_f32_e32 v69, 1.0, v69
	v_add_f32_e32 v70, 1.0, v70
	v_add_f32_e32 v71, 1.0, v71
	v_rcp_f32_e32 v68, v68
	v_rcp_f32_e32 v69, v69
	v_rcp_f32_e32 v70, v70
	v_rcp_f32_e32 v71, v71
	v_pk_add_f32 v[54:55], v[74:75], v[54:55]
	v_pk_mul_f32 v[50:51], v[50:51], v[68:69]
	v_pk_mul_f32 v[74:75], v[54:55], v[54:55]
	v_pk_mul_f32 v[52:53], v[52:53], v[70:71]
	flat_load_dwordx4 v[68:71], v[132:133]
	v_pk_add_f32 v[72:73], v[76:77], v[56:57]
	v_pk_mul_f32 v[56:57], v[48:49], v[48:49]
	v_fmamk_f32 v74, v74, 0xbdd2d3e7, v181
	v_fmamk_f32 v75, v75, 0xbdd2d3e7, v181
	v_fmamk_f32 v56, v56, 0xbdd2d3e7, v181
	v_fmamk_f32 v57, v57, 0xbdd2d3e7, v181
	v_mul_f32_e32 v74, v54, v74
	v_mul_f32_e32 v75, v55, v75
	v_mul_f32_e32 v56, v48, v56
	v_mul_f32_e32 v57, v49, v57
	v_exp_f32_e32 v74, v74
	v_exp_f32_e32 v75, v75
	v_exp_f32_e32 v56, v56
	v_exp_f32_e32 v57, v57
	v_add_f32_e32 v74, 1.0, v74
	v_add_f32_e32 v75, 1.0, v75
	v_add_f32_e32 v56, 1.0, v56
	v_add_f32_e32 v57, 1.0, v57
	v_rcp_f32_e32 v74, v74
	v_rcp_f32_e32 v75, v75
	v_rcp_f32_e32 v56, v56
	v_rcp_f32_e32 v57, v57
	v_pk_add_f32 v[44:45], v[32:33], v[44:45]
	v_pk_mul_f32 v[54:55], v[54:55], v[74:75]
	v_pk_add_f32 v[74:75], v[78:79], v[58:59]
	v_pk_mul_f32 v[48:49], v[48:49], v[56:57]
	v_pk_mul_f32 v[56:57], v[74:75], v[74:75]
	v_pk_mul_f32 v[32:33], v[44:45], v[44:45]
	v_fmamk_f32 v56, v56, 0xbdd2d3e7, v181
	v_mul_f32_e32 v56, v74, v56
	v_fmamk_f32 v57, v57, 0xbdd2d3e7, v181
	v_exp_f32_e32 v56, v56
	v_mul_f32_e32 v57, v75, v57
	v_fmamk_f32 v32, v32, 0xbdd2d3e7, v181
	v_exp_f32_e32 v57, v57
	v_mul_f32_e32 v32, v44, v32
	v_exp_f32_e32 v32, v32
	v_add_f32_e32 v56, 1.0, v56
	v_rcp_f32_e32 v78, v56
	v_add_f32_e32 v56, 1.0, v57
	v_rcp_f32_e32 v79, v56
	v_add_f32_e32 v56, 1.0, v32
	v_fmamk_f32 v32, v33, 0xbdd2d3e7, v181
	v_mul_f32_e32 v32, v45, v32
	v_exp_f32_e32 v57, v32
	v_pk_add_f32 v[32:33], v[62:63], v[46:47]
	v_pk_mul_f32 v[76:77], v[72:73], v[72:73]
	v_pk_add_f32 v[46:47], v[34:35], v[32:33]
	v_fmamk_f32 v76, v76, 0xbdd2d3e7, v181
	v_pk_mul_f32 v[32:33], v[46:47], v[46:47]
	v_fmamk_f32 v77, v77, 0xbdd2d3e7, v181
	v_fmamk_f32 v32, v32, 0xbdd2d3e7, v181
	v_mul_f32_e32 v32, v46, v32
	v_exp_f32_e32 v32, v32
	v_mul_f32_e32 v76, v72, v76
	v_mul_f32_e32 v77, v73, v77
	v_exp_f32_e32 v76, v76
	v_add_f32_e32 v90, 1.0, v32
	v_fmamk_f32 v32, v33, 0xbdd2d3e7, v181
	v_mul_f32_e32 v32, v47, v32
	v_exp_f32_e32 v77, v77
	v_exp_f32_e32 v91, v32
	v_add_f32_e32 v34, 1.0, v57
	v_rcp_f32_e32 v89, v34
	v_cvt_pk_bf16_f32 v32, v48, v49
	v_cvt_pk_bf16_f32 v33, v50, v51
	v_cvt_pk_bf16_f32 v34, v52, v53
	v_cvt_pk_bf16_f32 v35, v54, v55
	v_add_f32_e32 v76, 1.0, v76
	v_add_f32_e32 v77, 1.0, v77
	v_rcp_f32_e32 v88, v56
	v_mfma_f32_32x32x16_bf16 v[48:63], v[36:39], v[32:35], 0
	v_add_f32_e32 v37, 1.0, v91
	v_add_f32_e64 v0, v84, v0
	v_add_f32_e64 v1, v85, v1
	v_rcp_f32_e32 v76, v76
	v_rcp_f32_e32 v77, v77
	v_rcp_f32_e32 v36, v90
	v_rcp_f32_e32 v37, v37
	v_pk_mul_f32 v[16:17], v[0:1], v[0:1]
	v_pk_mul_f32 v[72:73], v[72:73], v[76:77]
	v_fmamk_f32 v16, v16, 0xbdd2d3e7, v181
	v_fmamk_f32 v17, v17, 0xbdd2d3e7, v181
	v_mul_f32_e32 v16, v0, v16
	v_mul_f32_e32 v17, v1, v17
	v_exp_f32_e32 v16, v16
	v_exp_f32_e32 v17, v17
	v_pk_mul_f32 v[76:77], v[44:45], v[88:89]
	v_pk_mul_f32 v[88:89], v[46:47], v[36:37]
	v_mfma_f32_32x32x16_bf16 v[32:47], v[40:43], v[32:35], 0
	v_mul_f32_e64 v74, v74, v78
	v_mul_f32_e64 v75, v75, v79
	v_add_f32_e32 v16, 1.0, v16
	v_add_f32_e32 v17, 1.0, v17
	v_cvt_pk_bf16_f32 v72, v72, v73
	v_cvt_pk_bf16_f32 v73, v74, v75
	v_cvt_pk_bf16_f32 v74, v76, v77
	flat_load_dwordx4 v[76:79], v[134:135]
	v_rcp_f32_e32 v16, v16
	v_rcp_f32_e32 v17, v17
	v_cvt_pk_bf16_f32 v75, v88, v89
	s_waitcnt vmcnt(0) lgkmcnt(0)
	v_pk_add_f32 v[68:69], v[68:69], v[4:5]
	v_pk_add_f32 v[8:9], v[76:77], v[8:9]
	v_mfma_f32_32x32x16_bf16 v[48:63], v[64:67], v[72:75], v[48:63]
	v_mul_f32_e64 v4, v68, v68
	v_mul_f32_e64 v5, v69, v69
	v_mul_f32_e64 v24, v8, v8
	v_mul_f32_e64 v25, v9, v9
	v_fmamk_f32 v4, v4, 0xbdd2d3e7, v181
	v_mul_f32_e32 v4, v68, v4
	v_exp_f32_e32 v4, v4
	v_fmamk_f32 v24, v24, 0xbdd2d3e7, v181
	v_fmamk_f32 v25, v25, 0xbdd2d3e7, v181
	v_mfma_f32_32x32x16_bf16 v[32:47], v[80:83], v[72:75], v[32:47]
	v_mul_f32_e64 v72, v0, v16
	v_mul_f32_e64 v73, v1, v17
	v_add_f32_e64 v0, v18, v2
	v_add_f32_e64 v1, v19, v3
	v_add_f32_e32 v18, 1.0, v4
	v_pk_add_f32 v[74:75], v[86:87], v[0:1]
	v_fmamk_f32 v4, v5, 0xbdd2d3e7, v181
	v_pk_mul_f32 v[16:17], v[74:75], v[74:75]
	v_mul_f32_e32 v4, v69, v4
	v_fmamk_f32 v0, v16, 0xbdd2d3e7, v181
	v_mul_f32_e32 v0, v74, v0
	v_exp_f32_e32 v16, v0
	flat_load_dwordx4 v[0:3], v[136:137]
	v_fmamk_f32 v17, v17, 0xbdd2d3e7, v181
	v_mul_f32_e32 v17, v75, v17
	v_exp_f32_e32 v17, v17
	v_add_f32_e32 v16, 1.0, v16
	v_rcp_f32_e32 v80, v16
	v_exp_f32_e32 v19, v4
	v_add_f32_e32 v16, 1.0, v17
	v_rcp_f32_e32 v81, v16
	ds_bpermute_b32 v16, v166, v6
	ds_bpermute_b32 v17, v166, v7
	global_load_dwordx2 v[4:5], v[124:125], off offset:64
	global_load_dwordx2 v[6:7], v[124:125], off offset:80
	v_rcp_f32_e32 v82, v18
	v_add_f32_e32 v18, 1.0, v19
	v_rcp_f32_e32 v83, v18
	s_waitcnt lgkmcnt(0)
	v_pk_add_f32 v[16:17], v[22:23], v[16:17]
	v_mul_f32_e32 v24, v8, v24
	v_pk_add_f32 v[70:71], v[70:71], v[16:17]
	global_load_dwordx2 v[16:17], v[138:139], off
	global_load_dwordx2 v[18:19], v[138:139], off offset:16
	v_pk_mul_f32 v[20:21], v[70:71], v[70:71]
	v_mul_f32_e32 v25, v9, v25
	v_fmamk_f32 v20, v20, 0xbdd2d3e7, v181
	v_mul_f32_e32 v20, v70, v20
	v_exp_f32_e32 v64, v20
	v_fmamk_f32 v20, v21, 0xbdd2d3e7, v181
	v_mul_f32_e32 v20, v71, v20
	v_exp_f32_e32 v65, v20
	v_add_f32_e32 v64, 1.0, v64
	v_rcp_f32_e32 v84, v64
	global_load_dwordx2 v[20:21], v[124:125], off offset:96
	global_load_dwordx2 v[22:23], v[124:125], off offset:112
	v_add_f32_e32 v64, 1.0, v65
	v_rcp_f32_e32 v85, v64
	global_load_dwordx2 v[64:65], v[140:141], off
	global_load_dwordx2 v[66:67], v[140:141], off offset:16
	v_exp_f32_e32 v24, v24
	v_exp_f32_e32 v25, v25
	v_pk_add_f32 v[10:11], v[78:79], v[10:11]
	v_pk_mul_f32 v[74:75], v[74:75], v[80:81]
	v_pk_mul_f32 v[26:27], v[10:11], v[10:11]
	v_add_f32_e32 v24, 1.0, v24
	v_fmamk_f32 v26, v26, 0xbdd2d3e7, v181
	v_add_f32_e32 v25, 1.0, v25
	v_mul_f32_e32 v26, v10, v26
	v_rcp_f32_e32 v24, v24
	v_rcp_f32_e32 v25, v25
	v_exp_f32_e32 v26, v26
	v_fmamk_f32 v27, v27, 0xbdd2d3e7, v181
	v_mul_f32_e32 v27, v11, v27
	v_exp_f32_e32 v27, v27
	v_pk_mul_f32 v[8:9], v[8:9], v[24:25]
	v_add_f32_e32 v24, 1.0, v26
	v_pk_mul_f32 v[68:69], v[68:69], v[82:83]
	v_add_f32_e32 v25, 1.0, v27
	v_pk_mul_f32 v[70:71], v[70:71], v[84:85]
	v_rcp_f32_e32 v24, v24
	v_rcp_f32_e32 v25, v25
	s_waitcnt vmcnt(0)
	v_pk_add_f32 v[12:13], v[0:1], v[12:13]
	s_nop 0
	v_pk_mul_f32 v[0:1], v[12:13], v[12:13]
	s_nop 0
	v_fmamk_f32 v0, v0, 0xbdd2d3e7, v181
	v_mul_f32_e32 v0, v12, v0
	v_exp_f32_e32 v26, v0
	v_fmamk_f32 v0, v1, 0xbdd2d3e7, v181
	v_mul_f32_e32 v0, v13, v0
	v_exp_f32_e32 v27, v0
	ds_bpermute_b32 v0, v166, v14
	ds_bpermute_b32 v1, v166, v15
	v_add_f32_e32 v14, 1.0, v26
	v_add_f32_e32 v15, 1.0, v27
	v_rcp_f32_e32 v14, v14
	v_rcp_f32_e32 v15, v15
	s_waitcnt lgkmcnt(0)
	v_pk_add_f32 v[0:1], v[30:31], v[0:1]
	s_nop 0
	v_pk_add_f32 v[26:27], v[2:3], v[0:1]
	v_cvt_pk_bf16_f32 v2, v68, v69
	v_pk_mul_f32 v[0:1], v[26:27], v[26:27]
	v_cvt_pk_bf16_f32 v3, v70, v71
	v_fmamk_f32 v0, v0, 0xbdd2d3e7, v181
	v_mul_f32_e32 v0, v26, v0
	v_exp_f32_e32 v28, v0
	v_fmamk_f32 v29, v1, 0xbdd2d3e7, v181
	v_cvt_pk_bf16_f32 v0, v72, v73
	v_cvt_pk_bf16_f32 v1, v74, v75
	s_nop 1
	v_mfma_f32_32x32x16_bf16 v[48:63], v[4:7], v[0:3], v[48:63]
	v_mul_f32_e32 v4, v27, v29
	v_exp_f32_e32 v5, v4
	v_add_f32_e32 v4, 1.0, v28
	v_rcp_f32_e32 v4, v4
	v_pk_mul_f32 v[6:7], v[12:13], v[14:15]
	v_add_f32_e32 v5, 1.0, v5
	v_rcp_f32_e32 v5, v5
	v_mfma_f32_32x32x16_bf16 v[32:47], v[16:19], v[0:3], v[32:47]
	v_mul_f32_e64 v2, v10, v24
	v_mul_f32_e64 v3, v11, v25
	v_cvt_pk_bf16_f32 v0, v8, v9
	v_mul_f32_e64 v4, v26, v4
	v_mul_f32_e64 v5, v27, v5
	v_cvt_pk_bf16_f32 v1, v2, v3
	v_cvt_pk_bf16_f32 v2, v6, v7
	v_cvt_pk_bf16_f32 v3, v4, v5
	s_nop 1
	v_mfma_f32_32x32x16_bf16 v[48:63], v[20:23], v[0:3], v[48:63]
	v_mfma_f32_32x32x16_bf16 v[32:47], v[64:67], v[0:3], v[32:47]
	v_add_u32_e32 v2, s9, v167
	v_cmp_gt_u32_e32 vcc, s33, v2
	s_and_b64 s[20:21], s[6:7], vcc
	s_and_saveexec_b64 s[18:19], s[20:21]
	s_cbranch_execz .LBB0_714
	s_lshl_b32 s8, s8, 11
	s_or_b32 s8, s8, s3
	v_or_b32_e32 v0, s8, v2
	v_lshlrev_b32_e32 v98, 7, v0
	s_nop 1
	v_cvt_pk_bf16_f32 v3, v48, v49
	v_cmp_gt_u32_e32 vcc, s31, v2
	v_cmp_lt_u32_e64 s[8:9], s34, v2
	v_lshl_add_u64 v[0:1], v[142:143], 0, v[98:99]
	v_cndmask_b32_e32 v98, 0, v3, vcc
	s_and_saveexec_b64 s[20:21], s[8:9]
	s_xor_b64 s[20:21], exec, s[20:21]
	s_cbranch_execnz .LBB0_738
	s_or_saveexec_b64 s[20:21], s[20:21]
	v_mov_b64_e32 v[2:3], 0
	s_xor_b64 exec, exec, s[20:21]
	s_cbranch_execnz .LBB0_739
